# sec 7.3: attention epilogue rows widened to 8 dwordx4 stores via v_permlane32_swap pairs (on v56)
# baseline (speedup 1.0000x reference)
.LBB0_222:
	s_or_b64 exec, exec, s[6:7]
	s_waitcnt lgkmcnt(0)
	s_barrier
	s_and_saveexec_b64 s[6:7], s[40:41]
	s_cbranch_execz .LBB0_195
	global_load_dwordx4 v[148:151], v[184:185], off
	global_load_dwordx4 v[152:155], v[184:185], off offset:32
	global_load_dwordx4 v[156:159], v[184:185], off offset:64
	global_load_dwordx4 v[162:165], v[184:185], off offset:96
	global_load_dwordx4 v[222:225], v[184:185], off offset:128
	global_load_dwordx4 v[236:239], v[184:185], off offset:160
	global_load_dwordx4 v[240:243], v[184:185], off offset:192
	global_load_dwordx4 v[244:247], v[184:185], off offset:224
	global_load_dwordx4 v[248:251], v[184:185], off offset:256
	global_load_dwordx4 v[230:233], v[184:185], off offset:288
	ds_read2st64_b32 v[78:79], v206 offset1:1
	ds_read2st64_b32 v[82:83], v206 offset0:2 offset1:3
	ds_read2st64_b32 v[96:97], v206 offset0:4 offset1:5
	ds_read2st64_b32 v[86:87], v206 offset0:6 offset1:7
	ds_read2st64_b32 v[100:101], v206 offset0:8 offset1:9
	ds_read2st64_b32 v[118:119], v206 offset0:10 offset1:11
	ds_read2st64_b32 v[120:121], v206 offset0:12 offset1:13
	ds_read2st64_b32 v[122:123], v206 offset0:14 offset1:15
	ds_read2st64_b32 v[124:125], v206 offset0:16 offset1:17
	ds_read2st64_b32 v[126:127], v206 offset0:18 offset1:19
	ds_read2st64_b32 v[128:129], v206 offset0:20 offset1:21
	ds_read2st64_b32 v[130:131], v206 offset0:22 offset1:23
	ds_read2st64_b32 v[132:133], v206 offset0:24 offset1:25
	ds_read2st64_b32 v[134:135], v206 offset0:26 offset1:27
	ds_read2st64_b32 v[114:115], v206 offset0:28 offset1:29
	ds_read2st64_b32 v[136:137], v206 offset0:30 offset1:31
	ds_read2st64_b32 v[110:111], v206 offset0:32 offset1:33
	ds_read2st64_b32 v[116:117], v206 offset0:34 offset1:35
	ds_read2st64_b32 v[106:107], v206 offset0:36 offset1:37
	ds_read2st64_b32 v[112:113], v206 offset0:38 offset1:39
	ds_read2st64_b32 v[102:103], v206 offset0:40 offset1:41
	ds_read2st64_b32 v[108:109], v206 offset0:42 offset1:43
	ds_read2st64_b32 v[98:99], v206 offset0:44 offset1:45
	ds_read2st64_b32 v[104:105], v206 offset0:46 offset1:47
	ds_read2st64_b32 v[90:91], v206 offset0:48 offset1:49
	ds_read2st64_b32 v[94:95], v206 offset0:50 offset1:51
	ds_read2st64_b32 v[76:77], v206 offset0:52 offset1:53
	ds_read2st64_b32 v[84:85], v206 offset0:54 offset1:55
	ds_read2st64_b32 v[74:75], v206 offset0:56 offset1:57
	ds_read2st64_b32 v[80:81], v206 offset0:58 offset1:59
	ds_read2st64_b32 v[64:65], v206 offset0:60 offset1:61
	s_waitcnt lgkmcnt(14)
	v_pk_mul_f32 v[82:83], v[186:187], v[82:83]
	s_lshl_b32 s4, s27, 1
	v_pk_fma_f32 v[82:83], v[50:51], v[70:71], v[82:83] op_sel_hi:[1,0,1] neg_lo:[0,0,1] neg_hi:[0,0,1]
	v_pk_mul_f32 v[50:51], v[186:187], v[78:79]
	s_waitcnt lgkmcnt(0)
	v_pk_mul_f32 v[64:65], v[186:187], v[64:65]
	v_pk_fma_f32 v[92:93], v[48:49], v[70:71], v[50:51] op_sel_hi:[1,0,1] neg_lo:[0,0,1] neg_hi:[0,0,1]
	v_pk_mul_f32 v[48:49], v[186:187], v[86:87]
	v_pk_fma_f32 v[64:65], v[12:13], v[70:71], v[64:65] op_sel_hi:[1,0,1] neg_lo:[0,0,1] neg_hi:[0,0,1]
	v_pk_fma_f32 v[86:87], v[54:55], v[70:71], v[48:49] op_sel_hi:[1,0,1] neg_lo:[0,0,1] neg_hi:[0,0,1]
	v_pk_mul_f32 v[48:49], v[186:187], v[96:97]
	ds_read_b32 v12, v206 offset:15872
	ds_read_b32 v13, v210
	v_pk_fma_f32 v[96:97], v[52:53], v[70:71], v[48:49] op_sel_hi:[1,0,1] neg_lo:[0,0,1] neg_hi:[0,0,1]
	v_pk_mul_f32 v[48:49], v[186:187], v[118:119]
	v_pk_mul_f32 v[140:141], v[92:93], v[92:93]
	v_pk_fma_f32 v[78:79], v[58:59], v[70:71], v[48:49] op_sel_hi:[1,0,1] neg_lo:[0,0,1] neg_hi:[0,0,1]
	v_pk_mul_f32 v[48:49], v[186:187], v[100:101]
	s_waitcnt lgkmcnt(0)
	v_pk_mul_f32 v[12:13], v[186:187], v[12:13]
	v_pk_fma_f32 v[100:101], v[56:57], v[70:71], v[48:49] op_sel_hi:[1,0,1] neg_lo:[0,0,1] neg_hi:[0,0,1]
	v_pk_mul_f32 v[48:49], v[186:187], v[122:123]
	v_pk_fma_f32 v[68:69], v[14:15], v[70:71], v[12:13] op_sel_hi:[1,0,1] neg_lo:[0,0,1] neg_hi:[0,0,1]
	v_pk_fma_f32 v[56:57], v[62:63], v[70:71], v[48:49] op_sel_hi:[1,0,1] neg_lo:[0,0,1] neg_hi:[0,0,1]
	v_pk_mul_f32 v[48:49], v[186:187], v[120:121]
	v_lshl_add_u64 v[12:13], s[20:21], 0, v[160:161]
	v_pk_fma_f32 v[60:61], v[60:61], v[70:71], v[48:49] op_sel_hi:[1,0,1] neg_lo:[0,0,1] neg_hi:[0,0,1]
	v_pk_mul_f32 v[48:49], v[186:187], v[126:127]
	v_lshl_add_u64 v[12:13], v[12:13], 0, s[4:5]
	v_pk_fma_f32 v[52:53], v[34:35], v[70:71], v[48:49] op_sel_hi:[1,0,1] neg_lo:[0,0,1] neg_hi:[0,0,1]
	v_pk_mul_f32 v[34:35], v[186:187], v[124:125]
	v_lshlrev_b32_e32 v160, 1, v180
	v_pk_fma_f32 v[58:59], v[32:33], v[70:71], v[34:35] op_sel_hi:[1,0,1] neg_lo:[0,0,1] neg_hi:[0,0,1]
	v_pk_mul_f32 v[32:33], v[186:187], v[130:131]
	v_lshl_add_u64 v[66:67], v[12:13], 0, v[160:161]
	v_pk_fma_f32 v[48:49], v[38:39], v[70:71], v[32:33] op_sel_hi:[1,0,1] neg_lo:[0,0,1] neg_hi:[0,0,1]
	v_pk_mul_f32 v[32:33], v[186:187], v[128:129]
	v_pk_fma_f32 v[54:55], v[36:37], v[70:71], v[32:33] op_sel_hi:[1,0,1] neg_lo:[0,0,1] neg_hi:[0,0,1]
	v_pk_mul_f32 v[32:33], v[186:187], v[134:135]
	v_pk_mul_f32 v[138:139], v[82:83], v[82:83]
	v_pk_fma_f32 v[42:43], v[42:43], v[70:71], v[32:33] op_sel_hi:[1,0,1] neg_lo:[0,0,1] neg_hi:[0,0,1]
	v_pk_mul_f32 v[32:33], v[186:187], v[132:133]
	v_pk_mul_f32 v[144:145], v[96:97], v[96:97]
	v_pk_fma_f32 v[50:51], v[40:41], v[70:71], v[32:33] op_sel_hi:[1,0,1] neg_lo:[0,0,1] neg_hi:[0,0,1]
	v_pk_mul_f32 v[32:33], v[186:187], v[136:137]
	v_pk_mul_f32 v[142:143], v[86:87], v[86:87]
	v_pk_fma_f32 v[38:39], v[46:47], v[70:71], v[32:33] op_sel_hi:[1,0,1] neg_lo:[0,0,1] neg_hi:[0,0,1]
	v_pk_mul_f32 v[32:33], v[186:187], v[114:115]
	v_pk_mul_f32 v[146:147], v[100:101], v[100:101]
	v_pk_fma_f32 v[44:45], v[44:45], v[70:71], v[32:33] op_sel_hi:[1,0,1] neg_lo:[0,0,1] neg_hi:[0,0,1]
	v_pk_mul_f32 v[32:33], v[186:187], v[116:117]
	v_pk_mul_f32 v[118:119], v[78:79], v[78:79]
	v_pk_fma_f32 v[34:35], v[18:19], v[70:71], v[32:33] op_sel_hi:[1,0,1] neg_lo:[0,0,1] neg_hi:[0,0,1]
	v_pk_mul_f32 v[18:19], v[186:187], v[110:111]
	v_pk_mul_f32 v[120:121], v[60:61], v[60:61]
	v_pk_fma_f32 v[40:41], v[16:17], v[70:71], v[18:19] op_sel_hi:[1,0,1] neg_lo:[0,0,1] neg_hi:[0,0,1]
	v_pk_mul_f32 v[16:17], v[186:187], v[112:113]
	v_pk_mul_f32 v[62:63], v[56:57], v[56:57]
	v_pk_fma_f32 v[32:33], v[22:23], v[70:71], v[16:17] op_sel_hi:[1,0,1] neg_lo:[0,0,1] neg_hi:[0,0,1]
	v_pk_mul_f32 v[16:17], v[186:187], v[106:107]
	v_pk_mul_f32 v[124:125], v[58:59], v[58:59]
	v_pk_fma_f32 v[36:37], v[20:21], v[70:71], v[16:17] op_sel_hi:[1,0,1] neg_lo:[0,0,1] neg_hi:[0,0,1]
	v_pk_mul_f32 v[16:17], v[186:187], v[108:109]
	v_pk_mul_f32 v[122:123], v[52:53], v[52:53]
	v_pk_fma_f32 v[22:23], v[26:27], v[70:71], v[16:17] op_sel_hi:[1,0,1] neg_lo:[0,0,1] neg_hi:[0,0,1]
	v_pk_mul_f32 v[16:17], v[186:187], v[102:103]
	v_pk_mul_f32 v[128:129], v[54:55], v[54:55]
	v_pk_fma_f32 v[26:27], v[24:25], v[70:71], v[16:17] op_sel_hi:[1,0,1] neg_lo:[0,0,1] neg_hi:[0,0,1]
	v_pk_mul_f32 v[16:17], v[186:187], v[104:105]
	v_pk_mul_f32 v[126:127], v[48:49], v[48:49]
	v_pk_fma_f32 v[18:19], v[30:31], v[70:71], v[16:17] op_sel_hi:[1,0,1] neg_lo:[0,0,1] neg_hi:[0,0,1]
	v_pk_mul_f32 v[16:17], v[186:187], v[98:99]
	v_pk_mul_f32 v[132:133], v[50:51], v[50:51]
	v_pk_fma_f32 v[24:25], v[28:29], v[70:71], v[16:17] op_sel_hi:[1,0,1] neg_lo:[0,0,1] neg_hi:[0,0,1]
	v_pk_mul_f32 v[16:17], v[186:187], v[94:95]
	v_pk_mul_f32 v[130:131], v[42:43], v[42:43]
	v_pk_fma_f32 v[16:17], v[2:3], v[70:71], v[16:17] op_sel_hi:[1,0,1] neg_lo:[0,0,1] neg_hi:[0,0,1]
	v_pk_mul_f32 v[2:3], v[186:187], v[90:91]
	v_pk_mul_f32 v[114:115], v[44:45], v[44:45]
	v_pk_fma_f32 v[20:21], v[0:1], v[70:71], v[2:3] op_sel_hi:[1,0,1] neg_lo:[0,0,1] neg_hi:[0,0,1]
	v_pk_mul_f32 v[0:1], v[186:187], v[84:85]
	v_pk_mul_f32 v[46:47], v[38:39], v[38:39]
	v_pk_fma_f32 v[2:3], v[6:7], v[70:71], v[0:1] op_sel_hi:[1,0,1] neg_lo:[0,0,1] neg_hi:[0,0,1]
	v_pk_mul_f32 v[0:1], v[186:187], v[76:77]
	v_pk_mul_f32 v[110:111], v[40:41], v[40:41]
	v_pk_fma_f32 v[6:7], v[4:5], v[70:71], v[0:1] op_sel_hi:[1,0,1] neg_lo:[0,0,1] neg_hi:[0,0,1]
	v_pk_mul_f32 v[0:1], v[186:187], v[80:81]
	v_pk_mul_f32 v[4:5], v[186:187], v[74:75]
	v_pk_fma_f32 v[0:1], v[10:11], v[70:71], v[0:1] op_sel_hi:[1,0,1] neg_lo:[0,0,1] neg_hi:[0,0,1]
	v_pk_fma_f32 v[4:5], v[8:9], v[70:71], v[4:5] op_sel_hi:[1,0,1] neg_lo:[0,0,1] neg_hi:[0,0,1]
	v_add_f32_e32 v70, v140, v141
	v_add_f32_e32 v70, v70, v138
	v_add_f32_e32 v70, v70, v139
	v_add_f32_e32 v70, v70, v144
	v_add_f32_e32 v70, v70, v145
	v_add_f32_e32 v70, v70, v142
	v_add_f32_e32 v70, v70, v143
	v_add_f32_e32 v70, v70, v146
	v_add_f32_e32 v70, v70, v147
	v_add_f32_e32 v70, v70, v118
	v_add_f32_e32 v70, v70, v119
	v_add_f32_e32 v70, v70, v120
	v_add_f32_e32 v70, v70, v121
	v_add_f32_e32 v62, v70, v62
	v_add_f32_e32 v62, v62, v63
	v_add_f32_e32 v62, v62, v124
	v_add_f32_e32 v62, v62, v125
	v_add_f32_e32 v62, v62, v122
	v_add_f32_e32 v62, v62, v123
	v_add_f32_e32 v62, v62, v128
	v_add_f32_e32 v62, v62, v129
	v_add_f32_e32 v62, v62, v126
	v_add_f32_e32 v62, v62, v127
	v_add_f32_e32 v62, v62, v132
	v_add_f32_e32 v62, v62, v133
	v_add_f32_e32 v62, v62, v130
	v_add_f32_e32 v62, v62, v131
	v_add_f32_e32 v62, v62, v114
	v_add_f32_e32 v62, v62, v115
	v_add_f32_e32 v46, v62, v46
	v_add_f32_e32 v46, v46, v47
	v_add_f32_e32 v46, v46, v110
	v_pk_mul_f32 v[116:117], v[34:35], v[34:35]
	v_add_f32_e32 v46, v46, v111
	v_add_f32_e32 v46, v46, v116
	v_pk_mul_f32 v[106:107], v[36:37], v[36:37]
	v_add_f32_e32 v46, v46, v117
	v_add_f32_e32 v46, v46, v106
	v_pk_mul_f32 v[112:113], v[32:33], v[32:33]
	v_add_f32_e32 v46, v46, v107
	v_add_f32_e32 v46, v46, v112
	v_pk_mul_f32 v[102:103], v[26:27], v[26:27]
	v_add_f32_e32 v46, v46, v113
	v_add_f32_e32 v46, v46, v102
	v_pk_mul_f32 v[108:109], v[22:23], v[22:23]
	v_add_f32_e32 v46, v46, v103
	v_add_f32_e32 v46, v46, v108
	v_pk_mul_f32 v[28:29], v[24:25], v[24:25]
	v_add_f32_e32 v46, v46, v109
	v_add_f32_e32 v28, v46, v28
	v_pk_mul_f32 v[30:31], v[18:19], v[18:19]
	v_add_f32_e32 v28, v28, v29
	v_add_f32_e32 v28, v28, v30
	v_pk_mul_f32 v[90:91], v[20:21], v[20:21]
	v_add_f32_e32 v28, v28, v31
	v_add_f32_e32 v28, v28, v90
	v_pk_mul_f32 v[94:95], v[16:17], v[16:17]
	v_add_f32_e32 v28, v28, v91
	v_add_f32_e32 v28, v28, v94
	v_pk_mul_f32 v[76:77], v[6:7], v[6:7]
	v_add_f32_e32 v28, v28, v95
	v_add_f32_e32 v28, v28, v76
	v_pk_mul_f32 v[84:85], v[2:3], v[2:3]
	v_add_f32_e32 v28, v28, v77
	v_add_f32_e32 v28, v28, v84
	v_pk_mul_f32 v[8:9], v[4:5], v[4:5]
	v_add_f32_e32 v28, v28, v85
	v_add_f32_e32 v8, v28, v8
	v_pk_mul_f32 v[10:11], v[0:1], v[0:1]
	v_add_f32_e32 v8, v8, v9
	v_add_f32_e32 v8, v8, v10
	v_pk_mul_f32 v[72:73], v[64:65], v[64:65]
	v_add_f32_e32 v8, v8, v11
	v_add_f32_e32 v8, v8, v72
	v_pk_mul_f32 v[88:89], v[68:69], v[68:69]
	v_add_f32_e32 v8, v8, v73
	v_add_f32_e32 v8, v8, v88
	v_add_f32_e32 v8, v8, v89
	global_load_dwordx4 v[102:105], v[184:185], off offset:320
	global_load_dwordx4 v[106:109], v[184:185], off offset:352
	global_load_dwordx4 v[110:113], v[184:185], off offset:384
	global_load_dwordx4 v[114:117], v[184:185], off offset:416
	global_load_dwordx4 v[118:121], v[184:185], off offset:448
	global_load_dwordx4 v[122:125], v[184:185], off offset:480
	ds_bpermute_b32 v9, v173, v8
	s_waitcnt lgkmcnt(0)
	v_add_f32_e32 v8, v8, v9
	v_fmamk_f32 v8, v8, 0x3c000000, v216
	v_cmp_gt_f32_e32 vcc, s29, v8
	v_mul_f32_e32 v9, 0x4b800000, v8
	s_nop 0
	v_cndmask_b32_e32 v8, v8, v9, vcc
	v_rsq_f32_e32 v8, v8
	s_nop 0
	v_mul_f32_e32 v9, 0x45800000, v8
	v_cndmask_b32_e32 v8, v8, v9, vcc
	v_mul_f32_e32 v8, v171, v8
	v_mbcnt_lo_u32_b32 v80, -1, 0
	v_mbcnt_hi_u32_b32 v80, -1, v80
	v_lshrrev_b32_e32 v80, 5, v80
	v_lshlrev_b32_e32 v80, 3, v80
	v_add_co_u32_e32 v66, vcc, v80, v66
	s_nop 1
	v_addc_co_u32_e32 v67, vcc, 0, v67, vcc
	v_pk_mul_f32 v[10:11], v[92:93], v[8:9] op_sel_hi:[1,0]
	v_pk_mul_f32 v[12:13], v[82:83], v[8:9] op_sel_hi:[1,0]
	s_waitcnt vmcnt(15)
	v_pk_mul_f32 v[10:11], v[148:149], v[10:11]
	v_pk_mul_f32 v[12:13], v[150:151], v[12:13]
	v_pk_mul_f32 v[70:71], v[96:97], v[8:9] op_sel_hi:[1,0]
	v_pk_mul_f32 v[72:73], v[86:87], v[8:9] op_sel_hi:[1,0]
	s_waitcnt vmcnt(14)
	v_pk_mul_f32 v[70:71], v[152:153], v[70:71]
	v_pk_mul_f32 v[72:73], v[154:155], v[72:73]
	v_cvt_pk_bf16_f32 v10, v10, v11
	v_cvt_pk_bf16_f32 v11, v12, v13
	v_cvt_pk_bf16_f32 v12, v70, v71
	v_cvt_pk_bf16_f32 v13, v72, v73
	s_nop 1
	v_permlane32_swap_b32_e32 v10, v12
	v_permlane32_swap_b32_e32 v11, v13
	global_store_dwordx4 v[66:67], v[10:13], off
	v_pk_mul_f32 v[74:75], v[100:101], v[8:9] op_sel_hi:[1,0]
	v_pk_mul_f32 v[76:77], v[78:79], v[8:9] op_sel_hi:[1,0]
	s_waitcnt vmcnt(14)
	v_pk_mul_f32 v[74:75], v[156:157], v[74:75]
	v_pk_mul_f32 v[76:77], v[158:159], v[76:77]
	v_pk_mul_f32 v[70:71], v[60:61], v[8:9] op_sel_hi:[1,0]
	v_pk_mul_f32 v[72:73], v[56:57], v[8:9] op_sel_hi:[1,0]
	s_waitcnt vmcnt(13)
	v_pk_mul_f32 v[70:71], v[162:163], v[70:71]
	v_pk_mul_f32 v[72:73], v[164:165], v[72:73]
	v_cvt_pk_bf16_f32 v74, v74, v75
	v_cvt_pk_bf16_f32 v75, v76, v77
	v_cvt_pk_bf16_f32 v76, v70, v71
	v_cvt_pk_bf16_f32 v77, v72, v73
	s_nop 1
	v_permlane32_swap_b32_e32 v74, v76
	v_permlane32_swap_b32_e32 v75, v77
	global_store_dwordx4 v[66:67], v[74:77], off offset:32
	v_pk_mul_f32 v[10:11], v[58:59], v[8:9] op_sel_hi:[1,0]
	v_pk_mul_f32 v[12:13], v[52:53], v[8:9] op_sel_hi:[1,0]
	s_waitcnt vmcnt(13)
	v_pk_mul_f32 v[10:11], v[222:223], v[10:11]
	v_pk_mul_f32 v[12:13], v[224:225], v[12:13]
	v_pk_mul_f32 v[70:71], v[54:55], v[8:9] op_sel_hi:[1,0]
	v_pk_mul_f32 v[72:73], v[48:49], v[8:9] op_sel_hi:[1,0]
	s_waitcnt vmcnt(12)
	v_pk_mul_f32 v[70:71], v[236:237], v[70:71]
	v_pk_mul_f32 v[72:73], v[238:239], v[72:73]
	v_cvt_pk_bf16_f32 v10, v10, v11
	v_cvt_pk_bf16_f32 v11, v12, v13
	v_cvt_pk_bf16_f32 v12, v70, v71
	v_cvt_pk_bf16_f32 v13, v72, v73
	s_nop 1
	v_permlane32_swap_b32_e32 v10, v12
	v_permlane32_swap_b32_e32 v11, v13
	global_store_dwordx4 v[66:67], v[10:13], off offset:64
	v_pk_mul_f32 v[74:75], v[50:51], v[8:9] op_sel_hi:[1,0]
	v_pk_mul_f32 v[76:77], v[42:43], v[8:9] op_sel_hi:[1,0]
	s_waitcnt vmcnt(12)
	v_pk_mul_f32 v[74:75], v[240:241], v[74:75]
	v_pk_mul_f32 v[76:77], v[242:243], v[76:77]
	v_pk_mul_f32 v[70:71], v[44:45], v[8:9] op_sel_hi:[1,0]
	v_pk_mul_f32 v[72:73], v[38:39], v[8:9] op_sel_hi:[1,0]
	s_waitcnt vmcnt(11)
	v_pk_mul_f32 v[70:71], v[244:245], v[70:71]
	v_pk_mul_f32 v[72:73], v[246:247], v[72:73]
	v_cvt_pk_bf16_f32 v74, v74, v75
	v_cvt_pk_bf16_f32 v75, v76, v77
	v_cvt_pk_bf16_f32 v76, v70, v71
	v_cvt_pk_bf16_f32 v77, v72, v73
	s_nop 1
	v_permlane32_swap_b32_e32 v74, v76
	v_permlane32_swap_b32_e32 v75, v77
	global_store_dwordx4 v[66:67], v[74:77], off offset:96
	v_pk_mul_f32 v[10:11], v[40:41], v[8:9] op_sel_hi:[1,0]
	v_pk_mul_f32 v[12:13], v[34:35], v[8:9] op_sel_hi:[1,0]
	s_waitcnt vmcnt(11)
	v_pk_mul_f32 v[10:11], v[248:249], v[10:11]
	v_pk_mul_f32 v[12:13], v[250:251], v[12:13]
	v_pk_mul_f32 v[70:71], v[36:37], v[8:9] op_sel_hi:[1,0]
	v_pk_mul_f32 v[72:73], v[32:33], v[8:9] op_sel_hi:[1,0]
	s_waitcnt vmcnt(10)
	v_pk_mul_f32 v[70:71], v[230:231], v[70:71]
	v_pk_mul_f32 v[72:73], v[232:233], v[72:73]
	v_cvt_pk_bf16_f32 v10, v10, v11
	v_cvt_pk_bf16_f32 v11, v12, v13
	v_cvt_pk_bf16_f32 v12, v70, v71
	v_cvt_pk_bf16_f32 v13, v72, v73
	s_nop 1
	v_permlane32_swap_b32_e32 v10, v12
	v_permlane32_swap_b32_e32 v11, v13
	global_store_dwordx4 v[66:67], v[10:13], off offset:128
	v_pk_mul_f32 v[74:75], v[26:27], v[8:9] op_sel_hi:[1,0]
	v_pk_mul_f32 v[76:77], v[22:23], v[8:9] op_sel_hi:[1,0]
	s_waitcnt vmcnt(10)
	v_pk_mul_f32 v[74:75], v[102:103], v[74:75]
	v_pk_mul_f32 v[76:77], v[104:105], v[76:77]
	v_pk_mul_f32 v[70:71], v[24:25], v[8:9] op_sel_hi:[1,0]
	v_pk_mul_f32 v[72:73], v[18:19], v[8:9] op_sel_hi:[1,0]
	s_waitcnt vmcnt(9)
	v_pk_mul_f32 v[70:71], v[106:107], v[70:71]
	v_pk_mul_f32 v[72:73], v[108:109], v[72:73]
	v_cvt_pk_bf16_f32 v74, v74, v75
	v_cvt_pk_bf16_f32 v75, v76, v77
	v_cvt_pk_bf16_f32 v76, v70, v71
	v_cvt_pk_bf16_f32 v77, v72, v73
	s_nop 1
	v_permlane32_swap_b32_e32 v74, v76
	v_permlane32_swap_b32_e32 v75, v77
	global_store_dwordx4 v[66:67], v[74:77], off offset:160
	v_pk_mul_f32 v[10:11], v[20:21], v[8:9] op_sel_hi:[1,0]
	v_pk_mul_f32 v[12:13], v[16:17], v[8:9] op_sel_hi:[1,0]
	s_waitcnt vmcnt(9)
	v_pk_mul_f32 v[10:11], v[110:111], v[10:11]
	v_pk_mul_f32 v[12:13], v[112:113], v[12:13]
	v_pk_mul_f32 v[70:71], v[6:7], v[8:9] op_sel_hi:[1,0]
	v_pk_mul_f32 v[72:73], v[2:3], v[8:9] op_sel_hi:[1,0]
	s_waitcnt vmcnt(8)
	v_pk_mul_f32 v[70:71], v[114:115], v[70:71]
	v_pk_mul_f32 v[72:73], v[116:117], v[72:73]
	v_cvt_pk_bf16_f32 v10, v10, v11
	v_cvt_pk_bf16_f32 v11, v12, v13
	v_cvt_pk_bf16_f32 v12, v70, v71
	v_cvt_pk_bf16_f32 v13, v72, v73
	s_nop 1
	v_permlane32_swap_b32_e32 v10, v12
	v_permlane32_swap_b32_e32 v11, v13
	global_store_dwordx4 v[66:67], v[10:13], off offset:192
	v_pk_mul_f32 v[74:75], v[4:5], v[8:9] op_sel_hi:[1,0]
	v_pk_mul_f32 v[76:77], v[0:1], v[8:9] op_sel_hi:[1,0]
	s_waitcnt vmcnt(8)
	v_pk_mul_f32 v[74:75], v[118:119], v[74:75]
	v_pk_mul_f32 v[76:77], v[120:121], v[76:77]
	v_pk_mul_f32 v[70:71], v[64:65], v[8:9] op_sel_hi:[1,0]
	v_pk_mul_f32 v[72:73], v[68:69], v[8:9] op_sel_hi:[1,0]
	s_waitcnt vmcnt(7)
	v_pk_mul_f32 v[70:71], v[122:123], v[70:71]
	v_pk_mul_f32 v[72:73], v[124:125], v[72:73]
	v_cvt_pk_bf16_f32 v74, v74, v75
	v_cvt_pk_bf16_f32 v75, v76, v77
	v_cvt_pk_bf16_f32 v76, v70, v71
	v_cvt_pk_bf16_f32 v77, v72, v73
	s_nop 1
	v_permlane32_swap_b32_e32 v74, v76
	v_permlane32_swap_b32_e32 v75, v77
	global_store_dwordx4 v[66:67], v[74:77], off offset:224
	s_branch .LBB0_195
